# GEMM k-loops: the first MFMA's two LDS fragments are requested first and waited on alone (counted lgkmcnt) instead of waiting for three of the six reads
# baseline (speedup 1.0000x reference)
; template <class Epi>
; __device__ __forceinline__ void gemm_tile64(const bf16_t* A, const bf16_t* Bt, int tm, int tn, const Epi& epi, char* smem, const float* ssq, int nparts) {
;     ...
;     auto compute = [&]() {
; #pragma unroll
;         for (int ks = 0; ks < 2; ++ks) {
;             bf16x8 af[4], bfr[4];
; #pragma unroll
;             for (int m = 0; m < 4; ++m) { const int r = wr * 64 + m * 16 + fr; af[m] = *(const bf16x8*)(sA + r * 64 + (((ks * 4 + fq) ^ ((r >> 1) & 7)) * 8)); }
; #pragma unroll
;             for (int n = 0; n < 4; ++n) { const int r = wc * 64 + n * 16 + fr; bfr[n] = *(const bf16x8*)(sB + r * 64 + (((ks * 4 + fq) ^ ((r >> 1) & 7)) * 8)); }
; #pragma unroll
;             for (int m = 0; m < 4; ++m)
; #pragma unroll
;                 for (int n = 0; n < 4; ++n) acc[m][n] = __builtin_amdgcn_mfma_f32_16x16x32_bf16(bfr[n], af[m], acc[m][n], 0, 0, 0);
;         }
;     };
;     Slab s0;
;     gload(0, s0);
;     for (int kt = 0; kt < 16; ++kt) {
;         __syncthreads(); sstore(s0); __syncthreads();
;         gload(min(kt + 1, 15), s0);
;         compute();
;     __device__ __forceinline__ void operator()(const f32x4 (&acc)[4][4], int tm, int tn, int wr, int wc, int fr, int fq, const float* sRs) const {
;     ...
;             const float rs = sRs[rl];
;             if (tn == 0 && wc == 0 && fq == 0) rstd2[(size_t)tm * 128 + rl] = rs;
.LBB0_51:
	s_waitcnt lgkmcnt(0)
	s_barrier
	s_waitcnt vmcnt(7)
	ds_write_b128 v100, v[64:67]
	s_waitcnt vmcnt(6)
	ds_write_b128 v101, v[68:71] offset:16384
	s_waitcnt vmcnt(5)
	ds_write_b128 v102, v[72:75]
	s_waitcnt vmcnt(4)
	ds_write_b128 v103, v[76:79] offset:16384
	s_waitcnt vmcnt(3)
	ds_write_b128 v104, v[156:159]
	s_waitcnt vmcnt(2)
	ds_write_b128 v105, v[160:163] offset:16384
	s_waitcnt vmcnt(1)
	ds_write_b128 v106, v[148:151]
	s_waitcnt vmcnt(0)
	ds_write_b128 v107, v[152:155] offset:16384
	s_add_i32 s13, s13, 1
	s_waitcnt lgkmcnt(0)
	s_barrier
	s_setprio 2
	ds_read_b128 v[80:83], v109 offset:16384
	ds_read_b128 v[88:91], v108
	ds_read_b128 v[84:87], v109 offset:18432
	ds_read_b128 v[92:95], v108 offset:2048
	ds_read_b128 v[116:119], v109 offset:20480
	ds_read_b128 v[120:123], v109 offset:22528
	s_cmp_eq_u32 s13, 17
	s_cbranch_scc1 .Lgs_nopf
	global_load_dwordx4 v[64:67], v135, s[98:99]
	global_load_dwordx4 v[68:71], v135, s[20:21]
	global_load_dwordx4 v[72:75], v136, s[98:99]
	global_load_dwordx4 v[76:79], v136, s[20:21]
	global_load_dwordx4 v[156:159], v137, s[98:99]
	global_load_dwordx4 v[160:163], v137, s[20:21]
	global_load_dwordx4 v[148:151], v138, s[98:99]
	global_load_dwordx4 v[152:155], v138, s[20:21]
	s_add_u32 s98, s98, 0x80
	s_addc_u32 s99, s99, 0
	s_add_u32 s20, s20, 0x80
	s_addc_u32 s21, s21, 0
.Lgs_nopf:
	s_waitcnt lgkmcnt(4)
	v_mfma_f32_16x16x32_bf16 v[60:63], v[80:83], v[88:91], v[60:63]
	s_waitcnt lgkmcnt(3)
	v_mfma_f32_16x16x32_bf16 v[56:59], v[84:87], v[88:91], v[56:59]
	s_waitcnt lgkmcnt(1)
	v_mfma_f32_16x16x32_bf16 v[52:55], v[116:119], v[88:91], v[52:55]
	s_waitcnt lgkmcnt(0)
	v_mfma_f32_16x16x32_bf16 v[48:51], v[120:123], v[88:91], v[48:51]
	v_mfma_f32_16x16x32_bf16 v[44:47], v[80:83], v[92:95], v[44:47]
	v_mfma_f32_16x16x32_bf16 v[40:43], v[84:87], v[92:95], v[40:43]
	v_mfma_f32_16x16x32_bf16 v[36:39], v[116:119], v[92:95], v[36:39]
	v_mfma_f32_16x16x32_bf16 v[32:35], v[120:123], v[92:95], v[32:35]
	ds_read_b128 v[88:91], v108 offset:4096
	ds_read_b128 v[92:95], v108 offset:6144
	s_waitcnt lgkmcnt(1)
	v_mfma_f32_16x16x32_bf16 v[28:31], v[80:83], v[88:91], v[28:31]
	v_mfma_f32_16x16x32_bf16 v[24:27], v[84:87], v[88:91], v[24:27]
	v_mfma_f32_16x16x32_bf16 v[20:23], v[116:119], v[88:91], v[20:23]
	v_mfma_f32_16x16x32_bf16 v[12:15], v[120:123], v[88:91], v[12:15]
	s_waitcnt lgkmcnt(0)
	v_mfma_f32_16x16x32_bf16 v[0:3], v[80:83], v[92:95], v[0:3]
	v_mfma_f32_16x16x32_bf16 v[16:19], v[84:87], v[92:95], v[16:19]
	ds_read_b128 v[80:83], v111 offset:16384
	ds_read_b128 v[84:87], v111 offset:18432
	v_mfma_f32_16x16x32_bf16 v[8:11], v[116:119], v[92:95], v[8:11]
	v_mfma_f32_16x16x32_bf16 v[4:7], v[120:123], v[92:95], v[4:7]
	ds_read_b128 v[88:91], v110
	ds_read_b128 v[92:95], v110 offset:2048
	ds_read_b128 v[116:119], v111 offset:20480
	ds_read_b128 v[120:123], v111 offset:22528
	s_waitcnt lgkmcnt(3)
	v_mfma_f32_16x16x32_bf16 v[60:63], v[80:83], v[88:91], v[60:63]
	v_mfma_f32_16x16x32_bf16 v[56:59], v[84:87], v[88:91], v[56:59]
	s_waitcnt lgkmcnt(1)
	v_mfma_f32_16x16x32_bf16 v[52:55], v[116:119], v[88:91], v[52:55]
	s_waitcnt lgkmcnt(0)
	v_mfma_f32_16x16x32_bf16 v[48:51], v[120:123], v[88:91], v[48:51]
	ds_read_b128 v[88:91], v110 offset:4096
	ds_read_b128 v[144:147], v110 offset:6144
	v_mfma_f32_16x16x32_bf16 v[44:47], v[80:83], v[92:95], v[44:47]
	v_mfma_f32_16x16x32_bf16 v[40:43], v[84:87], v[92:95], v[40:43]
	v_mfma_f32_16x16x32_bf16 v[36:39], v[116:119], v[92:95], v[36:39]
	v_mfma_f32_16x16x32_bf16 v[32:35], v[120:123], v[92:95], v[32:35]
	s_waitcnt lgkmcnt(1)
	v_mfma_f32_16x16x32_bf16 v[28:31], v[80:83], v[88:91], v[28:31]
	v_mfma_f32_16x16x32_bf16 v[24:27], v[84:87], v[88:91], v[24:27]
	v_mfma_f32_16x16x32_bf16 v[20:23], v[116:119], v[88:91], v[20:23]
	v_mfma_f32_16x16x32_bf16 v[12:15], v[120:123], v[88:91], v[12:15]
	s_waitcnt lgkmcnt(0)
	v_mfma_f32_16x16x32_bf16 v[0:3], v[80:83], v[144:147], v[0:3]
	v_mfma_f32_16x16x32_bf16 v[16:19], v[84:87], v[144:147], v[16:19]
	v_mfma_f32_16x16x32_bf16 v[8:11], v[116:119], v[144:147], v[8:11]
	v_mfma_f32_16x16x32_bf16 v[4:7], v[120:123], v[144:147], v[4:7]
	s_setprio 0
	s_cmp_eq_u32 s13, 17
	s_cbranch_scc0 .LBB0_51
	s_mov_b32 s21, 0
	s_movk_i32 s20, 0x780
	s_mov_b32 s14, 15
	v_lshl_or_b32 v64, v97, 6, v96
	v_lshlrev_b32_e32 v67, 2, v64
	ds_read_b32 v66, v67 offset:32768
	v_or3_b32 v65, v98, s22, v99
	v_cmp_eq_u32_e32 vcc, 0, v65
	s_lshl_b32 s13, s12, 9
	v_ashrrev_i32_e32 v65, 31, v64
	s_and_saveexec_b64 s[24:25], vcc
	s_cbranch_execz .LBB0_54
	v_readlane_b32 s36, v165, 42
	v_readlane_b32 s40, v165, 46
	v_readlane_b32 s41, v165, 47
	s_add_u32 s14, s40, s13
	s_addc_u32 s15, s41, 0
	v_lshl_add_u64 v[68:69], v[64:65], 2, s[14:15]
	v_readlane_b32 s37, v165, 43
	v_readlane_b32 s38, v165, 44
	v_readlane_b32 s39, v165, 45
	v_readlane_b32 s42, v165, 48
	v_readlane_b32 s43, v165, 49
	v_readlane_b32 s44, v165, 50
	v_readlane_b32 s45, v165, 51
	v_readlane_b32 s46, v165, 52
	v_readlane_b32 s47, v165, 53
	v_readlane_b32 s48, v165, 54
	v_readlane_b32 s49, v165, 55
	v_readlane_b32 s50, v165, 56
	v_readlane_b32 s51, v165, 57
	s_waitcnt lgkmcnt(0)
	global_store_dword v[68:69], v66, off

; template <class Epi>
; __device__ __forceinline__ void gemm_tile64(const bf16_t* A, const bf16_t* Bt, int tm, int tn, const Epi& epi, char* smem, const float* ssq, int nparts) {
;     ...
;     auto compute = [&]() {
; #pragma unroll
;         for (int ks = 0; ks < 2; ++ks) {
;             bf16x8 af[4], bfr[4];
; #pragma unroll
;             for (int m = 0; m < 4; ++m) { const int r = wr * 64 + m * 16 + fr; af[m] = *(const bf16x8*)(sA + r * 64 + (((ks * 4 + fq) ^ ((r >> 1) & 7)) * 8)); }
; #pragma unroll
;             for (int n = 0; n < 4; ++n) { const int r = wc * 64 + n * 16 + fr; bfr[n] = *(const bf16x8*)(sB + r * 64 + (((ks * 4 + fq) ^ ((r >> 1) & 7)) * 8)); }
; #pragma unroll
;             for (int m = 0; m < 4; ++m)
; #pragma unroll
;                 for (int n = 0; n < 4; ++n) acc[m][n] = __builtin_amdgcn_mfma_f32_16x16x32_bf16(bfr[n], af[m], acc[m][n], 0, 0, 0);
;         }
;     };
;     Slab s0;
;     gload(0, s0);
;     for (int kt = 0; kt < 16; ++kt) {
;         __syncthreads(); sstore(s0); __syncthreads();
;         gload(min(kt + 1, 15), s0);
;         compute();
.LBB0_71:
	s_waitcnt lgkmcnt(0)
	s_barrier
	s_waitcnt vmcnt(7)
	ds_write_b128 v100, v[64:67]
	s_waitcnt vmcnt(6)
	ds_write_b128 v101, v[68:71] offset:16384
	s_waitcnt vmcnt(5)
	ds_write_b128 v102, v[72:75]
	s_waitcnt vmcnt(4)
	ds_write_b128 v103, v[76:79] offset:16384
	s_waitcnt vmcnt(3)
	ds_write_b128 v104, v[156:159]
	s_waitcnt vmcnt(2)
	ds_write_b128 v105, v[160:163] offset:16384
	s_waitcnt vmcnt(1)
	ds_write_b128 v106, v[148:151]
	s_waitcnt vmcnt(0)
	ds_write_b128 v107, v[152:155] offset:16384
	s_add_i32 s1, s1, 1
	s_waitcnt lgkmcnt(0)
	s_barrier
	s_setprio 2
	ds_read_b128 v[80:83], v109 offset:16384
	ds_read_b128 v[88:91], v108
	ds_read_b128 v[84:87], v109 offset:18432
	ds_read_b128 v[92:95], v108 offset:2048
	ds_read_b128 v[116:119], v109 offset:20480
	ds_read_b128 v[120:123], v109 offset:22528
	s_cmp_eq_u32 s1, 17
	s_cbranch_scc1 .Lgo_nopf
	global_load_dwordx4 v[64:67], v135, s[98:99]
	global_load_dwordx4 v[68:71], v135, s[20:21]
	global_load_dwordx4 v[72:75], v136, s[98:99]
	global_load_dwordx4 v[76:79], v136, s[20:21]
	global_load_dwordx4 v[156:159], v137, s[98:99]
	global_load_dwordx4 v[160:163], v137, s[20:21]
	global_load_dwordx4 v[148:151], v138, s[98:99]
	global_load_dwordx4 v[152:155], v138, s[20:21]
	s_add_u32 s98, s98, 0x80
	s_addc_u32 s99, s99, 0
	s_add_u32 s20, s20, 0x80
	s_addc_u32 s21, s21, 0
.Lgo_nopf:
	s_waitcnt lgkmcnt(4)
	v_mfma_f32_16x16x32_bf16 v[60:63], v[80:83], v[88:91], v[60:63]
	s_waitcnt lgkmcnt(3)
	v_mfma_f32_16x16x32_bf16 v[56:59], v[84:87], v[88:91], v[56:59]
	s_waitcnt lgkmcnt(1)
	v_mfma_f32_16x16x32_bf16 v[52:55], v[116:119], v[88:91], v[52:55]
	s_waitcnt lgkmcnt(0)
	v_mfma_f32_16x16x32_bf16 v[48:51], v[120:123], v[88:91], v[48:51]
	v_mfma_f32_16x16x32_bf16 v[44:47], v[80:83], v[92:95], v[44:47]
	v_mfma_f32_16x16x32_bf16 v[40:43], v[84:87], v[92:95], v[40:43]
	v_mfma_f32_16x16x32_bf16 v[36:39], v[116:119], v[92:95], v[36:39]
	v_mfma_f32_16x16x32_bf16 v[32:35], v[120:123], v[92:95], v[32:35]
	ds_read_b128 v[88:91], v108 offset:4096
	ds_read_b128 v[92:95], v108 offset:6144
	s_waitcnt lgkmcnt(1)
	v_mfma_f32_16x16x32_bf16 v[28:31], v[80:83], v[88:91], v[28:31]
	v_mfma_f32_16x16x32_bf16 v[24:27], v[84:87], v[88:91], v[24:27]
	v_mfma_f32_16x16x32_bf16 v[20:23], v[116:119], v[88:91], v[20:23]
	v_mfma_f32_16x16x32_bf16 v[16:19], v[120:123], v[88:91], v[16:19]
	s_waitcnt lgkmcnt(0)
	v_mfma_f32_16x16x32_bf16 v[4:7], v[80:83], v[92:95], v[4:7]
	v_mfma_f32_16x16x32_bf16 v[12:15], v[84:87], v[92:95], v[12:15]
	ds_read_b128 v[80:83], v111 offset:16384
	ds_read_b128 v[84:87], v111 offset:18432
	v_mfma_f32_16x16x32_bf16 v[8:11], v[116:119], v[92:95], v[8:11]
	v_mfma_f32_16x16x32_bf16 v[0:3], v[120:123], v[92:95], v[0:3]
	ds_read_b128 v[88:91], v110
	ds_read_b128 v[92:95], v110 offset:2048
	ds_read_b128 v[116:119], v111 offset:20480
	ds_read_b128 v[120:123], v111 offset:22528
	s_waitcnt lgkmcnt(3)
	v_mfma_f32_16x16x32_bf16 v[60:63], v[80:83], v[88:91], v[60:63]
	v_mfma_f32_16x16x32_bf16 v[56:59], v[84:87], v[88:91], v[56:59]
	s_waitcnt lgkmcnt(1)
	v_mfma_f32_16x16x32_bf16 v[52:55], v[116:119], v[88:91], v[52:55]
	s_waitcnt lgkmcnt(0)
	v_mfma_f32_16x16x32_bf16 v[48:51], v[120:123], v[88:91], v[48:51]
	ds_read_b128 v[88:91], v110 offset:4096
	ds_read_b128 v[144:147], v110 offset:6144
	v_mfma_f32_16x16x32_bf16 v[44:47], v[80:83], v[92:95], v[44:47]
	v_mfma_f32_16x16x32_bf16 v[40:43], v[84:87], v[92:95], v[40:43]
	v_mfma_f32_16x16x32_bf16 v[36:39], v[116:119], v[92:95], v[36:39]
	v_mfma_f32_16x16x32_bf16 v[32:35], v[120:123], v[92:95], v[32:35]
	s_waitcnt lgkmcnt(1)
	v_mfma_f32_16x16x32_bf16 v[28:31], v[80:83], v[88:91], v[28:31]
	v_mfma_f32_16x16x32_bf16 v[24:27], v[84:87], v[88:91], v[24:27]
	v_mfma_f32_16x16x32_bf16 v[20:23], v[116:119], v[88:91], v[20:23]
	v_mfma_f32_16x16x32_bf16 v[16:19], v[120:123], v[88:91], v[16:19]
	s_waitcnt lgkmcnt(0)
	v_mfma_f32_16x16x32_bf16 v[4:7], v[80:83], v[144:147], v[4:7]
	v_mfma_f32_16x16x32_bf16 v[12:15], v[84:87], v[144:147], v[12:15]
	v_mfma_f32_16x16x32_bf16 v[8:11], v[116:119], v[144:147], v[8:11]
	v_mfma_f32_16x16x32_bf16 v[0:3], v[120:123], v[144:147], v[0:3]
	s_setprio 0
	s_cmp_eq_u32 s1, 17
	s_cbranch_scc0 .LBB0_71
; __device__ __forceinline__ unsigned pk_bf16(float lo, float hi) { unsigned r; asm("v_cvt_pk_bf16_f32 %0, %1, %2" : "=v"(r) : "v"(lo), "v"(hi)); return r; }
;     __device__ __forceinline__ void operator()(const f32x4 (&acc)[4][4], int tm, int tn, int wr, int wc, int fr, int fq, const float*) const {
;     ...
;         for (int m = 0; m < 4; ++m) {
;             const size_t row = (size_t)tm * 128 + wr * 64 + m * 16 + fr;
;             f32x4 o[4]; float sq = 0.f;
; #pragma unroll
;             for (int n = 0; n < 4; ++n) {
;                 o[n] = *(const f32x4*)(xin + row * 1024 + col0 + n * 4) + acc[m][n];
;                 *(f32x4*)(xout + row * 1024 + col0 + n * 4) = o[n];
;                 sq += o[n][0] * o[n][0] + o[n][1] * o[n][1] + o[n][2] * o[n][2] + o[n][3] * o[n][3];
;             }
;             u32x4 w0, w1;
;             w0.x = pk_bf16(o[0][0], o[0][1]); w0.y = pk_bf16(o[0][2], o[0][3]); w0.z = pk_bf16(o[1][0], o[1][1]); w0.w = pk_bf16(o[1][2], o[1][3]);
;             w1.x = pk_bf16(o[2][0], o[2][1]); w1.y = pk_bf16(o[2][2], o[2][3]); w1.z = pk_bf16(o[3][0], o[3][1]); w1.w = pk_bf16(o[3][2], o[3][3]);
;             *(u32x4*)(xb + row * 1024 + col0) = w0; *(u32x4*)(xb + row * 1024 + col0 + 8) = w1;
;             sq += __shfl_xor(sq, 16); sq += __shfl_xor(sq, 32);
;             if (fq == 0) ssq[(size_t)(tn * 2 + wc) * T + row] = sq;
;         }
	s_mov_b32 s21, 0
	s_movk_i32 s20, 0x780
	s_mov_b32 s13, 15
	v_lshlrev_b32_e32 v66, 6, v99
	s_lshl_b32 s20, s12, 7
	v_ashrrev_i32_e32 v67, 31, v66
	s_lshl_b32 s1, s0, 7
	v_lshlrev_b32_e32 v64, 6, v96
	v_lshlrev_b32_e32 v65, 4, v97
	v_lshl_add_u64 v[66:67], s[20:21], 0, v[66:67]
	v_or3_b32 v64, v64, s1, v65
	v_or_b32_e32 v66, v66, v98
	v_lshl_or_b32 v68, s0, 1, v96
	v_ashrrev_i32_e32 v65, 31, v64
	v_ashrrev_i32_e32 v69, 31, v68
	v_lshlrev_b64 v[76:77], 12, v[66:67]
	v_lshlrev_b64 v[70:71], 17, v[68:69]
	v_lshl_add_u64 v[72:73], s[22:23], 0, v[76:77]
	v_lshlrev_b64 v[68:69], 2, v[64:65]
	v_lshl_add_u64 v[78:79], v[72:73], 0, v[68:69]
	global_load_dwordx4 v[82:85], v[78:79], off
	global_load_dwordx4 v[86:89], v[78:79], off offset:16
	global_load_dwordx4 v[90:93], v[78:79], off offset:32
	global_load_dwordx4 v[116:119], v[78:79], off offset:48
	v_add_co_u32_e32 v94, vcc, 0x10000, v78
	s_nop 1
	v_addc_co_u32_e32 v95, vcc, 0, v79, vcc
	global_load_dwordx4 v[120:123], v[94:95], off
	global_load_dwordx4 v[144:147], v[94:95], off offset:16
	global_load_dwordx4 v[148:151], v[94:95], off offset:32
	global_load_dwordx4 v[152:155], v[94:95], off offset:48
	v_add_co_u32_e32 v94, vcc, 0x20000, v78
	s_nop 1
	v_addc_co_u32_e32 v95, vcc, 0, v79, vcc
	global_load_dwordx4 v[156:159], v[94:95], off
	global_load_dwordx4 v[160:163], v[94:95], off offset:16
	global_load_dwordx4 v[100:103], v[94:95], off offset:32
	global_load_dwordx4 v[104:107], v[94:95], off offset:48
	v_add_co_u32_e32 v94, vcc, 0x30000, v78
	s_nop 1
	v_addc_co_u32_e32 v95, vcc, 0, v79, vcc
	global_load_dwordx4 v[108:111], v[94:95], off
	global_load_dwordx4 v[136:139], v[94:95], off offset:16
	global_load_dwordx4 v[140:143], v[94:95], off offset:32
	global_load_dwordx4 v[112:115], v[94:95], off offset:48
	v_readlane_b32 s36, v165, 42
	v_readlane_b32 s46, v165, 52
	v_readlane_b32 s47, v165, 53
	v_cmp_lt_i32_e64 s[0:1], v134, v132
	v_readlane_b32 s50, v165, 56
	v_readlane_b32 s51, v165, 57
	v_cmp_eq_u32_e32 vcc, 0, v97
	v_readlane_b32 s37, v165, 43
	v_readlane_b32 s38, v165, 44
	v_readlane_b32 s39, v165, 45
	v_readlane_b32 s40, v165, 46
	v_readlane_b32 s41, v165, 47
	v_readlane_b32 s42, v165, 48
	v_readlane_b32 s43, v165, 49
	v_readlane_b32 s44, v165, 50
	v_readlane_b32 s45, v165, 51
	v_readlane_b32 s48, v165, 54
	v_readlane_b32 s49, v165, 55
	s_waitcnt vmcnt(0)
	v_pk_add_f32 v[60:61], v[60:61], v[82:83]
	v_lshl_add_u64 v[72:73], s[82:83], 0, v[76:77]
	v_pk_add_f32 v[62:63], v[62:63], v[84:85]
	v_lshl_add_u64 v[76:77], v[72:73], 0, v[68:69]
	global_store_dwordx4 v[76:77], v[60:63], off
	v_mul_f32_e32 v80, v61, v61
	v_fmac_f32_e32 v80, v60, v60
	v_fmac_f32_e32 v80, v62, v62
	v_fmac_f32_e32 v80, v63, v63
	v_cvt_pk_bf16_f32 v60, v60, v61
	v_cvt_pk_bf16_f32 v61, v62, v63
	v_pk_add_f32 v[56:57], v[56:57], v[86:87]
	s_nop 0
	v_mul_f32_e32 v72, v57, v57
	v_pk_add_f32 v[58:59], v[58:59], v[88:89]
	v_fmac_f32_e32 v72, v56, v56
	v_fmac_f32_e32 v72, v58, v58
	global_store_dwordx4 v[76:77], v[56:59], off offset:16
	v_fmac_f32_e32 v72, v59, v59
	v_add_f32_e32 v80, v80, v72
	v_cvt_pk_bf16_f32 v62, v56, v57
	v_cvt_pk_bf16_f32 v63, v58, v59
	v_pk_add_f32 v[52:53], v[52:53], v[90:91]
	s_nop 0
	v_mul_f32_e32 v72, v53, v53
	v_pk_add_f32 v[54:55], v[54:55], v[92:93]
	v_fmac_f32_e32 v72, v52, v52
	v_fmac_f32_e32 v72, v54, v54
	global_store_dwordx4 v[76:77], v[52:55], off offset:32
	v_fmac_f32_e32 v72, v55, v55
	v_add_f32_e32 v80, v80, v72
	v_cvt_pk_bf16_f32 v52, v52, v53
	v_cvt_pk_bf16_f32 v53, v54, v55
	v_pk_add_f32 v[48:49], v[48:49], v[116:117]
	v_pk_add_f32 v[50:51], v[50:51], v[118:119]
	v_mul_f32_e32 v72, v49, v49
	global_store_dwordx4 v[76:77], v[48:51], off offset:48
	v_fmac_f32_e32 v72, v48, v48
	v_cvt_pk_bf16_f32 v54, v48, v49
	v_fmac_f32_e32 v72, v50, v50
	v_lshlrev_b64 v[48:49], 11, v[66:67]
	v_lshl_add_u64 v[48:49], s[46:47], 0, v[48:49]
	v_lshl_add_u64 v[48:49], v[64:65], 1, v[48:49]
	v_fmac_f32_e32 v72, v51, v51
	v_cvt_pk_bf16_f32 v55, v50, v51
	global_store_dwordx4 v[48:49], v[60:63], off
	global_store_dwordx4 v[48:49], v[52:55], off offset:16
	v_cndmask_b32_e64 v48, v130, v134, s[0:1]
	v_add_f32_e32 v72, v80, v72
	v_lshlrev_b32_e32 v50, 2, v48
	ds_bpermute_b32 v48, v50, v72
	v_cmp_lt_i32_e64 s[0:1], v133, v132
	s_waitcnt lgkmcnt(0)
	v_add_f32_e32 v52, v72, v48
	v_cndmask_b32_e64 v48, v130, v133, s[0:1]
	v_lshlrev_b32_e32 v51, 2, v48
	ds_bpermute_b32 v53, v51, v52
	v_lshl_add_u64 v[48:49], s[50:51], 0, v[70:71]
	v_lshl_add_u64 v[48:49], v[66:67], 2, v[48:49]
	s_and_saveexec_b64 s[0:1], vcc
	s_cbranch_execz .LBB0_74
	s_waitcnt lgkmcnt(0)
	v_add_f32_e32 v52, v52, v53
	global_store_dword v[48:49], v52, off

; template <class Epi>
; __device__ __forceinline__ void gemm_tile64(const bf16_t* A, const bf16_t* Bt, int tm, int tn, const Epi& epi, char* smem, const float* ssq, int nparts) {
;     ...
;     auto gload = [&](int kt, Slab& sl) {
; #pragma unroll
;         for (int i = 0; i < 4; ++i) { sl.a[i] = *(const u32x4*)(Ap + (size_t)(32 * i) * K + kt * 64); sl.b[i] = *(const u32x4*)(Bp + (size_t)(32 * i) * K + kt * 64); }
;     };
;     auto sstore = [&](const Slab& sl) {
; #pragma unroll
;         for (int i = 0; i < 4; ++i) {
;             const int r = lrow + 32 * i;
;             *(u32x4*)(sA + r * 64 + ((lc8 ^ ((r >> 1) & 7)) * 8)) = sl.a[i];
;             const int rs = (r & 64) | (((r >> 2) & 3) << 4) | (((r >> 4) & 3) << 2) | (r & 3);
;             *(u32x4*)(sB + rs * 64 + ((lc8 ^ ((rs >> 1) & 7)) * 8)) = sl.b[i];
;         }
;     };
;     auto compute = [&]() {
; #pragma unroll
;         for (int ks = 0; ks < 2; ++ks) {
;             bf16x8 af[4], bfr[4];
; #pragma unroll
;             for (int m = 0; m < 4; ++m) { const int r = wr * 64 + m * 16 + fr; af[m] = *(const bf16x8*)(sA + r * 64 + (((ks * 4 + fq) ^ ((r >> 1) & 7)) * 8)); }
; #pragma unroll
;             for (int n = 0; n < 4; ++n) { const int r = wc * 64 + n * 16 + fr; bfr[n] = *(const bf16x8*)(sB + r * 64 + (((ks * 4 + fq) ^ ((r >> 1) & 7)) * 8)); }
; #pragma unroll
;             for (int m = 0; m < 4; ++m)
; #pragma unroll
;                 for (int n = 0; n < 4; ++n) acc[m][n] = __builtin_amdgcn_mfma_f32_16x16x32_bf16(bfr[n], af[m], acc[m][n], 0, 0, 0);
;         }
;     };
;     Slab s0;
;     gload(0, s0);
;     for (int kt = 0; kt < 16; ++kt) {
;         __syncthreads(); sstore(s0); __syncthreads();
;         gload(min(kt + 1, 15), s0);
.LBB0_376:
	s_waitcnt lgkmcnt(0)
	s_barrier
	s_waitcnt vmcnt(7)
	ds_write_b128 v100, v[64:67]
	s_waitcnt vmcnt(6)
	ds_write_b128 v101, v[68:71] offset:16384
	s_waitcnt vmcnt(5)
	ds_write_b128 v102, v[72:75]
	s_waitcnt vmcnt(4)
	ds_write_b128 v103, v[76:79] offset:16384
	s_waitcnt vmcnt(3)
	ds_write_b128 v104, v[156:159]
	s_waitcnt vmcnt(2)
	ds_write_b128 v105, v[160:163] offset:16384
	s_waitcnt vmcnt(1)
	ds_write_b128 v106, v[148:151]
	s_waitcnt vmcnt(0)
	ds_write_b128 v107, v[152:155] offset:16384
	s_add_i32 s0, s0, 1
	s_waitcnt lgkmcnt(0)
	s_barrier
	s_setprio 2
	ds_read_b128 v[80:83], v109 offset:16384
	ds_read_b128 v[88:91], v108
	ds_read_b128 v[84:87], v109 offset:18432
	ds_read_b128 v[92:95], v108 offset:2048
	ds_read_b128 v[116:119], v109 offset:20480
	ds_read_b128 v[120:123], v109 offset:22528
	s_cmp_eq_u32 s0, 17
	s_cbranch_scc1 .Lgi_nopf
	global_load_dwordx4 v[64:67], v135, s[98:99]
	global_load_dwordx4 v[68:71], v135, s[20:21]
	global_load_dwordx4 v[72:75], v136, s[98:99]
	global_load_dwordx4 v[76:79], v136, s[20:21]
	global_load_dwordx4 v[156:159], v137, s[98:99]
	global_load_dwordx4 v[160:163], v137, s[20:21]
	global_load_dwordx4 v[148:151], v138, s[98:99]
	global_load_dwordx4 v[152:155], v138, s[20:21]
	s_add_u32 s98, s98, 0x80
	s_addc_u32 s99, s99, 0
	s_add_u32 s20, s20, 0x80
	s_addc_u32 s21, s21, 0
; template <class Epi>
; __device__ __forceinline__ void gemm_tile64(const bf16_t* A, const bf16_t* Bt, int tm, int tn, const Epi& epi, char* smem, const float* ssq, int nparts) {
;     ...
;     auto compute = [&]() {
; #pragma unroll
;         for (int ks = 0; ks < 2; ++ks) {
;             bf16x8 af[4], bfr[4];
; #pragma unroll
;             for (int m = 0; m < 4; ++m) { const int r = wr * 64 + m * 16 + fr; af[m] = *(const bf16x8*)(sA + r * 64 + (((ks * 4 + fq) ^ ((r >> 1) & 7)) * 8)); }
; #pragma unroll
;             for (int n = 0; n < 4; ++n) { const int r = wc * 64 + n * 16 + fr; bfr[n] = *(const bf16x8*)(sB + r * 64 + (((ks * 4 + fq) ^ ((r >> 1) & 7)) * 8)); }
; #pragma unroll
;             for (int m = 0; m < 4; ++m)
; #pragma unroll
;                 for (int n = 0; n < 4; ++n) acc[m][n] = __builtin_amdgcn_mfma_f32_16x16x32_bf16(bfr[n], af[m], acc[m][n], 0, 0, 0);
;         }
.Lgi_nopf:
	s_waitcnt lgkmcnt(4)
	v_mfma_f32_16x16x32_bf16 v[60:63], v[80:83], v[88:91], v[60:63]
	s_waitcnt lgkmcnt(3)
	v_mfma_f32_16x16x32_bf16 v[56:59], v[84:87], v[88:91], v[56:59]
	s_waitcnt lgkmcnt(1)
	v_mfma_f32_16x16x32_bf16 v[52:55], v[116:119], v[88:91], v[52:55]
	s_waitcnt lgkmcnt(0)
	v_mfma_f32_16x16x32_bf16 v[48:51], v[120:123], v[88:91], v[48:51]
	v_mfma_f32_16x16x32_bf16 v[44:47], v[80:83], v[92:95], v[44:47]
	v_mfma_f32_16x16x32_bf16 v[40:43], v[84:87], v[92:95], v[40:43]
	v_mfma_f32_16x16x32_bf16 v[36:39], v[116:119], v[92:95], v[36:39]
	v_mfma_f32_16x16x32_bf16 v[32:35], v[120:123], v[92:95], v[32:35]
	ds_read_b128 v[88:91], v108 offset:4096
	ds_read_b128 v[92:95], v108 offset:6144
	s_waitcnt lgkmcnt(1)
	v_mfma_f32_16x16x32_bf16 v[28:31], v[80:83], v[88:91], v[28:31]
	v_mfma_f32_16x16x32_bf16 v[24:27], v[84:87], v[88:91], v[24:27]
	v_mfma_f32_16x16x32_bf16 v[16:19], v[116:119], v[88:91], v[16:19]
	v_mfma_f32_16x16x32_bf16 v[12:15], v[120:123], v[88:91], v[12:15]
	s_waitcnt lgkmcnt(0)
	v_mfma_f32_16x16x32_bf16 v[8:11], v[80:83], v[92:95], v[8:11]
	v_mfma_f32_16x16x32_bf16 v[20:23], v[84:87], v[92:95], v[20:23]
	ds_read_b128 v[80:83], v111 offset:16384
	ds_read_b128 v[84:87], v111 offset:18432
	v_mfma_f32_16x16x32_bf16 v[4:7], v[116:119], v[92:95], v[4:7]
	v_mfma_f32_16x16x32_bf16 v[0:3], v[120:123], v[92:95], v[0:3]
	ds_read_b128 v[88:91], v110
	ds_read_b128 v[92:95], v110 offset:2048
	ds_read_b128 v[116:119], v111 offset:20480
	ds_read_b128 v[120:123], v111 offset:22528
	s_waitcnt lgkmcnt(3)
	v_mfma_f32_16x16x32_bf16 v[60:63], v[80:83], v[88:91], v[60:63]
	v_mfma_f32_16x16x32_bf16 v[56:59], v[84:87], v[88:91], v[56:59]
	s_waitcnt lgkmcnt(1)
	v_mfma_f32_16x16x32_bf16 v[52:55], v[116:119], v[88:91], v[52:55]
	s_waitcnt lgkmcnt(0)
	v_mfma_f32_16x16x32_bf16 v[48:51], v[120:123], v[88:91], v[48:51]
	ds_read_b128 v[88:91], v110 offset:4096
	ds_read_b128 v[144:147], v110 offset:6144
	v_mfma_f32_16x16x32_bf16 v[44:47], v[80:83], v[92:95], v[44:47]
	v_mfma_f32_16x16x32_bf16 v[40:43], v[84:87], v[92:95], v[40:43]
	v_mfma_f32_16x16x32_bf16 v[36:39], v[116:119], v[92:95], v[36:39]
	v_mfma_f32_16x16x32_bf16 v[32:35], v[120:123], v[92:95], v[32:35]
	s_waitcnt lgkmcnt(1)
	v_mfma_f32_16x16x32_bf16 v[28:31], v[80:83], v[88:91], v[28:31]
	v_mfma_f32_16x16x32_bf16 v[24:27], v[84:87], v[88:91], v[24:27]
	v_mfma_f32_16x16x32_bf16 v[16:19], v[116:119], v[88:91], v[16:19]
	v_mfma_f32_16x16x32_bf16 v[12:15], v[120:123], v[88:91], v[12:15]
	s_waitcnt lgkmcnt(0)
	v_mfma_f32_16x16x32_bf16 v[8:11], v[80:83], v[144:147], v[8:11]
	v_mfma_f32_16x16x32_bf16 v[20:23], v[84:87], v[144:147], v[20:23]
	v_mfma_f32_16x16x32_bf16 v[4:7], v[116:119], v[144:147], v[4:7]
	v_mfma_f32_16x16x32_bf16 v[0:3], v[120:123], v[144:147], v[0:3]
	s_setprio 0
	s_cmp_eq_u32 s0, 17
	s_cbranch_scc0 .LBB0_376
	s_mov_b32 s21, 0
	s_movk_i32 s20, 0x780
	s_mov_b32 s1, 15
	s_cmp_lt_u32 s22, 8
	s_cbranch_scc0 .Lnq_skip
	v_mul_f32_e32 v64, v48, v48
	v_fmac_f32_e32 v64, v49, v49
	v_fmac_f32_e32 v64, v50, v50
	v_fmac_f32_e32 v64, v51, v51
	v_fmac_f32_e32 v64, v52, v52
	v_fmac_f32_e32 v64, v53, v53
	v_fmac_f32_e32 v64, v54, v54
	v_fmac_f32_e32 v64, v55, v55
	v_fmac_f32_e32 v64, v56, v56
	v_fmac_f32_e32 v64, v57, v57
	v_fmac_f32_e32 v64, v58, v58
	v_fmac_f32_e32 v64, v59, v59
	v_fmac_f32_e32 v64, v60, v60
	v_fmac_f32_e32 v64, v61, v61
	v_fmac_f32_e32 v64, v62, v62
	v_fmac_f32_e32 v64, v63, v63
	v_mul_f32_e32 v65, v32, v32
	v_fmac_f32_e32 v65, v33, v33
	v_fmac_f32_e32 v65, v34, v34
	v_fmac_f32_e32 v65, v35, v35
	v_fmac_f32_e32 v65, v36, v36
	v_fmac_f32_e32 v65, v37, v37
	v_fmac_f32_e32 v65, v38, v38
	v_fmac_f32_e32 v65, v39, v39
	v_fmac_f32_e32 v65, v40, v40
	v_fmac_f32_e32 v65, v41, v41
	v_fmac_f32_e32 v65, v42, v42
	v_fmac_f32_e32 v65, v43, v43
	v_fmac_f32_e32 v65, v44, v44
	v_fmac_f32_e32 v65, v45, v45
	v_fmac_f32_e32 v65, v46, v46
	v_fmac_f32_e32 v65, v47, v47
	v_mul_f32_e32 v66, v12, v12
	v_fmac_f32_e32 v66, v13, v13
	v_fmac_f32_e32 v66, v14, v14
	v_fmac_f32_e32 v66, v15, v15
	v_fmac_f32_e32 v66, v16, v16
	v_fmac_f32_e32 v66, v17, v17
	v_fmac_f32_e32 v66, v18, v18
	v_fmac_f32_e32 v66, v19, v19
	v_fmac_f32_e32 v66, v24, v24
	v_fmac_f32_e32 v66, v25, v25
	v_fmac_f32_e32 v66, v26, v26
	v_fmac_f32_e32 v66, v27, v27
	v_fmac_f32_e32 v66, v28, v28
	v_fmac_f32_e32 v66, v29, v29
	v_fmac_f32_e32 v66, v30, v30
	v_fmac_f32_e32 v66, v31, v31
	v_mul_f32_e32 v67, v0, v0
	v_fmac_f32_e32 v67, v1, v1
	v_fmac_f32_e32 v67, v2, v2
	v_fmac_f32_e32 v67, v3, v3
	v_fmac_f32_e32 v67, v4, v4
	v_fmac_f32_e32 v67, v5, v5
	v_fmac_f32_e32 v67, v6, v6
	v_fmac_f32_e32 v67, v7, v7
	v_fmac_f32_e32 v67, v8, v8
	v_fmac_f32_e32 v67, v9, v9
	v_fmac_f32_e32 v67, v10, v10
	v_fmac_f32_e32 v67, v11, v11
	v_fmac_f32_e32 v67, v20, v20
	v_fmac_f32_e32 v67, v21, v21
	v_fmac_f32_e32 v67, v22, v22
	v_fmac_f32_e32 v67, v23, v23
	v_mov_b32_e32 v68, v64
	s_nop 1
	v_permlane16_swap_b32_e32 v68, v64
	v_add_f32_e32 v64, v64, v68
	v_mov_b32_e32 v68, v64
	s_nop 1
	v_permlane32_swap_b32_e32 v68, v64
	v_add_f32_e32 v64, v64, v68
	v_mov_b32_e32 v68, v65
	s_nop 1
	v_permlane16_swap_b32_e32 v68, v65
	v_add_f32_e32 v65, v65, v68
	v_mov_b32_e32 v68, v65
	s_nop 1
	v_permlane32_swap_b32_e32 v68, v65
	v_add_f32_e32 v65, v65, v68
	v_mov_b32_e32 v68, v66
	s_nop 1
	v_permlane16_swap_b32_e32 v68, v66
	v_add_f32_e32 v66, v66, v68
	v_mov_b32_e32 v68, v66
	s_nop 1
	v_permlane32_swap_b32_e32 v68, v66
	v_add_f32_e32 v66, v66, v68
	v_mov_b32_e32 v68, v67
	s_nop 1
	v_permlane16_swap_b32_e32 v68, v67
	v_add_f32_e32 v67, v67, v68
	v_mov_b32_e32 v68, v67
	s_nop 1
	v_permlane32_swap_b32_e32 v68, v67
	v_add_f32_e32 v67, v67, v68
	v_lshl_or_b32 v69, v96, 6, v98
	v_lshlrev_b32_e32 v69, 2, v69
	ds_read_b32 v70, v69 offset:32768
	ds_read_b32 v71, v69 offset:32832
	ds_read_b32 v72, v69 offset:32896
	ds_read_b32 v73, v69 offset:32960
	v_readlane_b32 s98, v165, 2
	v_readlane_b32 s99, v165, 3
	v_readlane_b32 s32, v167, 36
	s_waitcnt lgkmcnt(0)
	v_mul_f32_e32 v70, v70, v70
	v_mul_f32_e32 v64, v64, v70
	v_mul_f32_e32 v71, v71, v71
	v_mul_f32_e32 v65, v65, v71
	v_mul_f32_e32 v72, v72, v72
	v_mul_f32_e32 v66, v66, v72
	v_mul_f32_e32 v73, v73, v73
	v_mul_f32_e32 v67, v67, v73
	v_max3_f32 v64, v64, v65, v66
	v_max_f32_e32 v64, v64, v67
	s_mul_i32 s32, s32, 0xc00
	s_add_i32 s32, s32, 32
	v_mov_b32_e32 v69, s32
	s_and_b32 s32, s2, 7
	v_lshl_add_u32 v69, s32, 7, v69
	v_max_f32_dpp v64, v64, v64 row_ror:8 row_mask:0xf bank_mask:0xf
	s_lshr_b32 s32, s22, 2
	v_lshl_add_u32 v69, s32, 10, v69
	v_max_f32_dpp v64, v64, v64 row_ror:4 row_mask:0xf bank_mask:0xf
	s_and_b32 s32, s22, 3
	v_lshl_add_u32 v69, s32, 3, v69
	v_max_f32_dpp v64, v64, v64 quad_perm:[2,3,0,1] row_mask:0xf bank_mask:0xf
	v_lshl_add_u32 v69, v97, 2, v69
	v_cmp_eq_u32_e32 vcc, 0, v130
	v_max_f32_dpp v64, v64, v64 quad_perm:[1,0,3,2] row_mask:0xf bank_mask:0xf
	s_and_saveexec_b64 s[36:37], vcc
	global_atomic_umax v69, v64, s[98:99]
	s_or_b64 exec, exec, s[36:37]
